# attention V-phase: six of the eight S1 bf16 packs also moved into the exp loop
# baseline (speedup 1.0000x reference)
; __device__ __forceinline__ void expHalf(f32x16& p0) {
; #pragma unroll
;     for (int r = 0; r < 16; ++r) p0[r] = __builtin_amdgcn_exp2f(p0[r]);
; }
; __device__ __forceinline__ void finishSM(f32x16& p0, f32x16& p1, float& l_reg, bf16x8& pa0, bf16x8& pa1, bf16x8& pa2, bf16x8& pa3) {
;     float ps = 0;
; #pragma unroll
;     for (int r = 0; r < 16; ++r) ps += p0[r];
; #pragma unroll
;     for (int r = 0; r < 16; ++r) ps += p1[r];
;     l_reg += ps;
;     ...
;     PK4(p0, 0, pa0); PK4(p0, 8, pa1); PK4(p1, 0, pa2); PK4(p1, 8, pa3);
.Lat_far_g0l:
	v_exp_f32_e32 v112, v112
	v_exp_f32_e32 v113, v113
	v_exp_f32_e32 v114, v114
	v_add_f32_e32 v64, v64, v112
	v_exp_f32_e32 v115, v115
	v_add_f32_e32 v65, v65, v113
	v_exp_f32_e32 v116, v116
	v_add_f32_e32 v66, v66, v114
	v_exp_f32_e32 v117, v117
	v_add_f32_e32 v67, v67, v115
	v_exp_f32_e32 v118, v118
	v_add_f32_e32 v64, v64, v116
	v_exp_f32_e32 v119, v119
	v_add_f32_e32 v65, v65, v117
	v_exp_f32_e32 v120, v120
	v_add_f32_e32 v66, v66, v118
	v_exp_f32_e32 v121, v121
	v_add_f32_e32 v67, v67, v119
	v_exp_f32_e32 v122, v122
	v_add_f32_e32 v64, v64, v120
	v_exp_f32_e32 v123, v123
	v_add_f32_e32 v65, v65, v121
	v_exp_f32_e32 v124, v124
	v_add_f32_e32 v66, v66, v122
	v_exp_f32_e32 v125, v125
	v_add_f32_e32 v67, v67, v123
	v_exp_f32_e32 v126, v126
	v_add_f32_e32 v64, v64, v124
	v_exp_f32_e32 v127, v127
	v_add_f32_e32 v65, v65, v125
	v_exp_f32_e32 v192, v192
	v_add_f32_e32 v66, v66, v126
	v_cvt_pk_bf16_f32 v208, v112, v113
	v_exp_f32_e32 v193, v193
	v_add_f32_e32 v67, v67, v127
	v_cvt_pk_bf16_f32 v209, v114, v115
	v_exp_f32_e32 v194, v194
	v_add_f32_e32 v64, v64, v192
	v_cvt_pk_bf16_f32 v210, v116, v117
	v_exp_f32_e32 v195, v195
	v_add_f32_e32 v65, v65, v193
	v_cvt_pk_bf16_f32 v211, v118, v119
	v_exp_f32_e32 v196, v196
	v_add_f32_e32 v66, v66, v194
	v_cvt_pk_bf16_f32 v212, v120, v121
	v_exp_f32_e32 v197, v197
	v_add_f32_e32 v67, v67, v195
	v_cvt_pk_bf16_f32 v213, v122, v123
	v_exp_f32_e32 v198, v198
	v_add_f32_e32 v64, v64, v196
	v_cvt_pk_bf16_f32 v214, v124, v125
	v_exp_f32_e32 v199, v199
	v_add_f32_e32 v65, v65, v197
	v_cvt_pk_bf16_f32 v215, v126, v127
	v_exp_f32_e32 v200, v200
	v_add_f32_e32 v66, v66, v198
	v_exp_f32_e32 v201, v201
	v_add_f32_e32 v67, v67, v199
	v_exp_f32_e32 v202, v202
	v_add_f32_e32 v64, v64, v200
	v_cvt_pk_bf16_f32 v216, v192, v193
	v_exp_f32_e32 v203, v203
	v_add_f32_e32 v65, v65, v201
	v_cvt_pk_bf16_f32 v217, v194, v195
	v_exp_f32_e32 v204, v204
	v_add_f32_e32 v66, v66, v202
	v_cvt_pk_bf16_f32 v218, v196, v197
	v_exp_f32_e32 v205, v205
	v_add_f32_e32 v67, v67, v203
	v_cvt_pk_bf16_f32 v219, v198, v199
	v_exp_f32_e32 v206, v206
	v_add_f32_e32 v64, v64, v204
	v_cvt_pk_bf16_f32 v220, v200, v201
	v_exp_f32_e32 v207, v207
	v_add_f32_e32 v65, v65, v205
	v_cvt_pk_bf16_f32 v221, v202, v203
	v_add_f32_e32 v66, v66, v206
	v_add_f32_e32 v67, v67, v207
	v_cvt_pk_bf16_f32 v222, v204, v205
	v_cvt_pk_bf16_f32 v223, v206, v207
	s_add_i32 s99, s23, 64
	s_cmp_ge_i32 s99, s30
	s_cselect_b32 s6, s22, s98
	s_cmp_le_i32 s99, s29
	s_cselect_b32 s6, s21, s6
	s_nop 0
	s_cmp_lg_u32 s6, s9
	s_cbranch_scc0 .Lat_c0same_g0l
	s_mov_b32 s9, s6
	v_mov_b32_e32 v68, s9
	v_mov_b32_e32 v69, s9
	v_mov_b32_e32 v70, s9
	v_mov_b32_e32 v71, s9
	v_mov_b32_e32 v72, s9
	v_mov_b32_e32 v73, s9
	v_mov_b32_e32 v74, s9
	v_mov_b32_e32 v75, s9
	v_mov_b32_e32 v76, s9
	v_mov_b32_e32 v77, s9
	v_mov_b32_e32 v78, s9
	v_mov_b32_e32 v79, s9
	v_mov_b32_e32 v80, s9
	v_mov_b32_e32 v81, s9
	v_mov_b32_e32 v82, s9
	v_mov_b32_e32 v83, s9

; #define SBAR() __builtin_amdgcn_sched_barrier(0)
; #define PVLOAD(D0, X) do { X[0] = tr_read<v_rd_off(D0, 0, 0)>(vb); X[1] = tr_read<v_rd_off(D0, 0, 1)>(vb); X[2] = tr_read<v_rd_off(D0, 1, 0)>(vb); X[3] = tr_read<v_rd_off(D0, 1, 1)>(vb); \
;     X[4] = tr_read<v_rd_off(D0, 2, 0)>(vb); X[5] = tr_read<v_rd_off(D0, 2, 1)>(vb); X[6] = tr_read<v_rd_off(D0, 3, 0)>(vb); X[7] = tr_read<v_rd_off(D0, 3, 1)>(vb); } while (0)
; #define PVMMA(OD, X) do { OD = __builtin_amdgcn_mfma_f32_32x32x16_bf16(pa0, PVPK(X[0], X[1]), OD, 0, 0, 0); OD = __builtin_amdgcn_mfma_f32_32x32x16_bf16(pa1, PVPK(X[2], X[3]), OD, 0, 0, 0); \
;     OD = __builtin_amdgcn_mfma_f32_32x32x16_bf16(pa2, PVPK(X[4], X[5]), OD, 0, 0, 0); OD = __builtin_amdgcn_mfma_f32_32x32x16_bf16(pa3, PVPK(X[6], X[7]), OD, 0, 0, 0); } while (0)
; #define PVWAIT() do { asm volatile("s_waitcnt lgkmcnt(0)" ::: "memory"); SBAR(); } while (0)
; #define PVEXP(P, B, N) do { _Pragma("unroll") for (int r = (B); r < (B) + (N); ++r) P[r] = __builtin_amdgcn_exp2f(P[r]); } while (0)
; __device__ __forceinline__ void expHalf(f32x16& p0) {
; #pragma unroll
;     for (int r = 0; r < 16; ++r) p0[r] = __builtin_amdgcn_exp2f(p0[r]);
; }
; __device__ __forceinline__ void finishSM(f32x16& p0, f32x16& p1, float& l_reg, bf16x8& pa0, bf16x8& pa1, bf16x8& pa2, bf16x8& pa3) {
;     float ps = 0;
; #pragma unroll
;     for (int r = 0; r < 16; ++r) ps += p0[r];
; #pragma unroll
;     for (int r = 0; r < 16; ++r) ps += p1[r];
;     l_reg += ps;
;     ...
;     PK4(p0, 0, pa0); PK4(p0, 8, pa1); PK4(p1, 0, pa2); PK4(p1, 8, pa3);
; template <int NB> __device__ __forceinline__ void pv_blocks(f32x16* o, int vb, bf16x8 pa0, bf16x8 pa1, bf16x8 pa2, bf16x8 pa3, f32x16& pe0, f32x16& pe1) {
;     s16x4 x[8], y[8];
;     ...
;     PVLOAD(0, x); PVWAIT();
;     if (NB == 4) {
;         PVLOAD(1, y); SBAR(); PVMMA(o[0], x); PVEXP(pe0, 0, 8); SBAR(); PVWAIT();
;         PVLOAD(2, x); SBAR(); PVMMA(o[1], y); PVEXP(pe0, 8, 8); SBAR(); PVWAIT();
;         PVLOAD(3, y); SBAR(); PVMMA(o[2], x); PVEXP(pe1, 0, 8); SBAR(); PVWAIT();
;         PVMMA(o[3], y); PVEXP(pe1, 8, 8);
;     } else {
;         PVLOAD(1, y); SBAR(); PVMMA(o[0], x); PVEXP(pe0, 0, 16); SBAR(); PVWAIT();
;         PVMMA(o[1], y); PVEXP(pe1, 0, 16);
;     }
.Lat_far_g0p:
	v_exp_f32_e32 v112, v112
	v_exp_f32_e32 v113, v113
	v_exp_f32_e32 v114, v114
	v_add_f32_e32 v64, v64, v112
	v_exp_f32_e32 v115, v115
	v_add_f32_e32 v65, v65, v113
	v_exp_f32_e32 v116, v116
	v_add_f32_e32 v66, v66, v114
	v_exp_f32_e32 v117, v117
	v_add_f32_e32 v67, v67, v115
	v_exp_f32_e32 v118, v118
	v_add_f32_e32 v64, v64, v116
	v_exp_f32_e32 v119, v119
	v_add_f32_e32 v65, v65, v117
	v_exp_f32_e32 v120, v120
	v_add_f32_e32 v66, v66, v118
	v_exp_f32_e32 v121, v121
	v_add_f32_e32 v67, v67, v119
	v_exp_f32_e32 v122, v122
	v_add_f32_e32 v64, v64, v120
	v_exp_f32_e32 v123, v123
	v_add_f32_e32 v65, v65, v121
	v_exp_f32_e32 v124, v124
	v_add_f32_e32 v66, v66, v122
	v_exp_f32_e32 v125, v125
	v_add_f32_e32 v67, v67, v123
	v_exp_f32_e32 v126, v126
	v_add_f32_e32 v64, v64, v124
	v_exp_f32_e32 v127, v127
	v_add_f32_e32 v65, v65, v125
	v_exp_f32_e32 v192, v192
	v_add_f32_e32 v66, v66, v126
	v_cvt_pk_bf16_f32 v208, v112, v113
	v_exp_f32_e32 v193, v193
	v_add_f32_e32 v67, v67, v127
	v_cvt_pk_bf16_f32 v209, v114, v115
	v_exp_f32_e32 v194, v194
	v_add_f32_e32 v64, v64, v192
	v_cvt_pk_bf16_f32 v210, v116, v117
	v_exp_f32_e32 v195, v195
	v_add_f32_e32 v65, v65, v193
	v_cvt_pk_bf16_f32 v211, v118, v119
	v_exp_f32_e32 v196, v196
	v_add_f32_e32 v66, v66, v194
	v_cvt_pk_bf16_f32 v212, v120, v121
	v_exp_f32_e32 v197, v197
	v_add_f32_e32 v67, v67, v195
	v_cvt_pk_bf16_f32 v213, v122, v123
	v_exp_f32_e32 v198, v198
	v_add_f32_e32 v64, v64, v196
	v_cvt_pk_bf16_f32 v214, v124, v125
	v_exp_f32_e32 v199, v199
	v_add_f32_e32 v65, v65, v197
	v_cvt_pk_bf16_f32 v215, v126, v127
	v_exp_f32_e32 v200, v200
	v_add_f32_e32 v66, v66, v198
	v_exp_f32_e32 v201, v201
	v_add_f32_e32 v67, v67, v199
	v_exp_f32_e32 v202, v202
	v_add_f32_e32 v64, v64, v200
	v_cvt_pk_bf16_f32 v216, v192, v193
	v_exp_f32_e32 v203, v203
	v_add_f32_e32 v65, v65, v201
	v_cvt_pk_bf16_f32 v217, v194, v195
	v_exp_f32_e32 v204, v204
	v_add_f32_e32 v66, v66, v202
	v_cvt_pk_bf16_f32 v218, v196, v197
	v_exp_f32_e32 v205, v205
	v_add_f32_e32 v67, v67, v203
	v_cvt_pk_bf16_f32 v219, v198, v199
	v_exp_f32_e32 v206, v206
	v_add_f32_e32 v64, v64, v204
	v_cvt_pk_bf16_f32 v220, v200, v201
	v_exp_f32_e32 v207, v207
	v_add_f32_e32 v65, v65, v205
	v_cvt_pk_bf16_f32 v221, v202, v203
	v_add_f32_e32 v66, v66, v206
	v_add_f32_e32 v67, v67, v207
	v_cvt_pk_bf16_f32 v222, v204, v205
	v_cvt_pk_bf16_f32 v223, v206, v207
	s_nop 1
	s_waitcnt vmcnt(0)
	s_barrier
	s_setprio 0
	ds_read_b64_tr_b16 v[84:85], v168 offset:0
	ds_read_b64_tr_b16 v[86:87], v168 offset:2048
	ds_read_b64_tr_b16 v[88:89], v168 offset:4096
	ds_read_b64_tr_b16 v[90:91], v168 offset:6144
	ds_read_b64_tr_b16 v[92:93], v168 offset:8192
	ds_read_b64_tr_b16 v[94:95], v168 offset:10240
	ds_read_b64_tr_b16 v[128:129], v168 offset:12288
	ds_read_b64_tr_b16 v[130:131], v168 offset:14336
	ds_read_b64_tr_b16 v[132:133], v168 offset:512
	ds_read_b64_tr_b16 v[134:135], v168 offset:2560
	ds_read_b64_tr_b16 v[140:141], v168 offset:4608
	ds_read_b64_tr_b16 v[142:143], v168 offset:6656
	ds_read_b64_tr_b16 v[152:153], v168 offset:8704
	ds_read_b64_tr_b16 v[154:155], v168 offset:10752
	s_waitcnt lgkmcnt(12)
	v_mfma_f32_32x32x16_bf16 v[0:15], v[208:211], v[84:87], v[0:15]
	ds_read_b64_tr_b16 v[160:161], v168 offset:12800
	ds_read_b64_tr_b16 v[162:163], v168 offset:14848
	s_waitcnt lgkmcnt(12)
	v_mfma_f32_32x32x16_bf16 v[0:15], v[212:215], v[88:91], v[0:15]
	ds_read_b64_tr_b16 v[84:85], v168 offset:1024
	ds_read_b64_tr_b16 v[86:87], v168 offset:3072
	s_waitcnt lgkmcnt(12)
	v_mfma_f32_32x32x16_bf16 v[0:15], v[216:219], v[92:95], v[0:15]
	ds_read_b64_tr_b16 v[88:89], v168 offset:5120
	ds_read_b64_tr_b16 v[90:91], v168 offset:7168
	s_waitcnt lgkmcnt(12)
	v_mfma_f32_32x32x16_bf16 v[0:15], v[220:223], v[128:131], v[0:15]
	ds_read_b64_tr_b16 v[92:93], v168 offset:9216
	ds_read_b64_tr_b16 v[94:95], v168 offset:11264
	s_waitcnt lgkmcnt(12)
	v_mfma_f32_32x32x16_bf16 v[16:31], v[208:211], v[132:135], v[16:31]
	ds_read_b64_tr_b16 v[128:129], v168 offset:13312
	ds_read_b64_tr_b16 v[130:131], v168 offset:15360
	s_waitcnt lgkmcnt(12)
	v_mfma_f32_32x32x16_bf16 v[16:31], v[212:215], v[140:143], v[16:31]
	ds_read_b64_tr_b16 v[132:133], v168 offset:1536
	ds_read_b64_tr_b16 v[134:135], v168 offset:3584
	s_waitcnt lgkmcnt(12)
	v_mfma_f32_32x32x16_bf16 v[16:31], v[216:219], v[152:155], v[16:31]
	ds_read_b64_tr_b16 v[140:141], v168 offset:5632
	ds_read_b64_tr_b16 v[142:143], v168 offset:7680
	s_waitcnt lgkmcnt(12)
	v_mfma_f32_32x32x16_bf16 v[16:31], v[220:223], v[160:163], v[16:31]
	ds_read_b64_tr_b16 v[152:153], v168 offset:9728
	ds_read_b64_tr_b16 v[154:155], v168 offset:11776
	s_waitcnt lgkmcnt(12)
	v_mfma_f32_32x32x16_bf16 v[32:47], v[208:211], v[84:87], v[32:47]
	ds_read_b64_tr_b16 v[160:161], v168 offset:13824
	ds_read_b64_tr_b16 v[162:163], v168 offset:15872
	v_xor_b32_e32 v168, 0x4000, v168
	s_waitcnt lgkmcnt(12)
	v_mfma_f32_32x32x16_bf16 v[32:47], v[212:215], v[88:91], v[32:47]
	s_waitcnt lgkmcnt(10)
	v_mfma_f32_32x32x16_bf16 v[32:47], v[216:219], v[92:95], v[32:47]
	s_waitcnt lgkmcnt(8)
	v_mfma_f32_32x32x16_bf16 v[32:47], v[220:223], v[128:131], v[32:47]
	s_waitcnt lgkmcnt(6)
	v_mfma_f32_32x32x16_bf16 v[48:63], v[208:211], v[132:135], v[48:63]
	s_waitcnt lgkmcnt(4)
	v_mfma_f32_32x32x16_bf16 v[48:63], v[212:215], v[140:143], v[48:63]
	s_waitcnt lgkmcnt(2)
	v_mfma_f32_32x32x16_bf16 v[48:63], v[216:219], v[152:155], v[48:63]
	s_waitcnt lgkmcnt(0)
	v_mfma_f32_32x32x16_bf16 v[48:63], v[220:223], v[160:163], v[48:63]
	s_barrier
	s_barrier
	s_branch .Lat_done

; __device__ __forceinline__ void expHalf(f32x16& p0) {
; #pragma unroll
;     for (int r = 0; r < 16; ++r) p0[r] = __builtin_amdgcn_exp2f(p0[r]);
; }
; __device__ __forceinline__ void finishSM(f32x16& p0, f32x16& p1, float& l_reg, bf16x8& pa0, bf16x8& pa1, bf16x8& pa2, bf16x8& pa3) {
;     float ps = 0;
; #pragma unroll
;     for (int r = 0; r < 16; ++r) ps += p0[r];
; #pragma unroll
;     for (int r = 0; r < 16; ++r) ps += p1[r];
;     l_reg += ps;
;     ...
;     PK4(p0, 0, pa0); PK4(p0, 8, pa1); PK4(p1, 0, pa2); PK4(p1, 8, pa3);
.Lat_far_g1l:
	s_mov_b32 m0, s33
	s_add_u32 s7, s33, 0x2000
	global_load_lds_dwordx4 v171, s[26:27]
	v_exp_f32_e32 v112, v112
	v_exp_f32_e32 v113, v113
	v_exp_f32_e32 v114, v114
	v_add_f32_e32 v64, v64, v112
	v_exp_f32_e32 v115, v115
	v_add_f32_e32 v65, v65, v113
	v_exp_f32_e32 v116, v116
	v_add_f32_e32 v66, v66, v114
	v_exp_f32_e32 v117, v117
	v_add_f32_e32 v67, v67, v115
	v_exp_f32_e32 v118, v118
	v_add_f32_e32 v64, v64, v116
	v_exp_f32_e32 v119, v119
	v_add_f32_e32 v65, v65, v117
	s_mov_b32 m0, s7
	s_xor_b32 s33, s33, 0x4000
	global_load_lds_dwordx4 v172, s[26:27]
	s_add_u32 s26, s26, 0x50000
	s_addc_u32 s27, s27, 0
	v_exp_f32_e32 v120, v120
	v_add_f32_e32 v66, v66, v118
	v_exp_f32_e32 v121, v121
	v_add_f32_e32 v67, v67, v119
	v_exp_f32_e32 v122, v122
	v_add_f32_e32 v64, v64, v120
	v_exp_f32_e32 v123, v123
	v_add_f32_e32 v65, v65, v121
	v_exp_f32_e32 v124, v124
	v_add_f32_e32 v66, v66, v122
	v_exp_f32_e32 v125, v125
	v_add_f32_e32 v67, v67, v123
	v_exp_f32_e32 v126, v126
	v_add_f32_e32 v64, v64, v124
	v_exp_f32_e32 v127, v127
	v_add_f32_e32 v65, v65, v125
	s_mov_b32 m0, s31
	s_add_u32 s7, s31, 0x2000
	global_load_lds_dwordx4 v169, s[24:25]
	v_exp_f32_e32 v192, v192
	v_add_f32_e32 v66, v66, v126
	v_cvt_pk_bf16_f32 v208, v112, v113
	v_exp_f32_e32 v193, v193
	v_add_f32_e32 v67, v67, v127
	v_cvt_pk_bf16_f32 v209, v114, v115
	v_exp_f32_e32 v194, v194
	v_add_f32_e32 v64, v64, v192
	v_cvt_pk_bf16_f32 v210, v116, v117
	v_exp_f32_e32 v195, v195
	v_add_f32_e32 v65, v65, v193
	v_cvt_pk_bf16_f32 v211, v118, v119
	v_exp_f32_e32 v196, v196
	v_add_f32_e32 v66, v66, v194
	v_cvt_pk_bf16_f32 v212, v120, v121
	v_exp_f32_e32 v197, v197
	v_add_f32_e32 v67, v67, v195
	v_cvt_pk_bf16_f32 v213, v122, v123
	s_mov_b32 m0, s7
	s_add_u32 s31, s31, s100
	global_load_lds_dwordx4 v170, s[24:25]
	s_add_u32 s24, s24, 0x50000
	s_addc_u32 s25, s25, 0
	v_exp_f32_e32 v198, v198
	v_add_f32_e32 v64, v64, v196
	v_cvt_pk_bf16_f32 v214, v124, v125
	v_exp_f32_e32 v199, v199
	v_add_f32_e32 v65, v65, v197
	v_cvt_pk_bf16_f32 v215, v126, v127
	v_exp_f32_e32 v200, v200
	v_add_f32_e32 v66, v66, v198
	v_exp_f32_e32 v201, v201
	v_add_f32_e32 v67, v67, v199
	v_exp_f32_e32 v202, v202
	v_add_f32_e32 v64, v64, v200
	v_cvt_pk_bf16_f32 v216, v192, v193
	v_exp_f32_e32 v203, v203
	v_add_f32_e32 v65, v65, v201
	v_cvt_pk_bf16_f32 v217, v194, v195
	v_exp_f32_e32 v204, v204
	v_add_f32_e32 v66, v66, v202
	v_cvt_pk_bf16_f32 v218, v196, v197
	v_exp_f32_e32 v205, v205
	v_add_f32_e32 v67, v67, v203
	v_cvt_pk_bf16_f32 v219, v198, v199
	v_exp_f32_e32 v206, v206
	v_add_f32_e32 v64, v64, v204
	v_cvt_pk_bf16_f32 v220, v200, v201
	v_exp_f32_e32 v207, v207
	v_add_f32_e32 v65, v65, v205
	v_cvt_pk_bf16_f32 v221, v202, v203
	v_add_f32_e32 v66, v66, v206
	v_add_f32_e32 v67, v67, v207
	v_cvt_pk_bf16_f32 v222, v204, v205
	v_cvt_pk_bf16_f32 v223, v206, v207
	s_add_i32 s99, s23, 64
	s_cmp_ge_i32 s99, s30
	s_cselect_b32 s6, s22, s98
	s_cmp_le_i32 s99, s29
	s_cselect_b32 s6, s21, s6
	s_nop 0
	s_cmp_lg_u32 s6, s9
	s_cbranch_scc0 .Lat_c0same_g1l
	s_mov_b32 s9, s6
	v_mov_b32_e32 v68, s9
	v_mov_b32_e32 v69, s9
	v_mov_b32_e32 v70, s9
	v_mov_b32_e32 v71, s9
	v_mov_b32_e32 v72, s9
	v_mov_b32_e32 v73, s9
	v_mov_b32_e32 v74, s9
	v_mov_b32_e32 v75, s9
	v_mov_b32_e32 v76, s9
	v_mov_b32_e32 v77, s9
	v_mov_b32_e32 v78, s9
	v_mov_b32_e32 v79, s9
	v_mov_b32_e32 v80, s9
	v_mov_b32_e32 v81, s9
	v_mov_b32_e32 v82, s9
	v_mov_b32_e32 v83, s9

; #define SBAR() __builtin_amdgcn_sched_barrier(0)
; #define PVLOAD(D0, X) do { X[0] = tr_read<v_rd_off(D0, 0, 0)>(vb); X[1] = tr_read<v_rd_off(D0, 0, 1)>(vb); X[2] = tr_read<v_rd_off(D0, 1, 0)>(vb); X[3] = tr_read<v_rd_off(D0, 1, 1)>(vb); \
;     X[4] = tr_read<v_rd_off(D0, 2, 0)>(vb); X[5] = tr_read<v_rd_off(D0, 2, 1)>(vb); X[6] = tr_read<v_rd_off(D0, 3, 0)>(vb); X[7] = tr_read<v_rd_off(D0, 3, 1)>(vb); } while (0)
; #define PVMMA(OD, X) do { OD = __builtin_amdgcn_mfma_f32_32x32x16_bf16(pa0, PVPK(X[0], X[1]), OD, 0, 0, 0); OD = __builtin_amdgcn_mfma_f32_32x32x16_bf16(pa1, PVPK(X[2], X[3]), OD, 0, 0, 0); \
;     OD = __builtin_amdgcn_mfma_f32_32x32x16_bf16(pa2, PVPK(X[4], X[5]), OD, 0, 0, 0); OD = __builtin_amdgcn_mfma_f32_32x32x16_bf16(pa3, PVPK(X[6], X[7]), OD, 0, 0, 0); } while (0)
; #define PVWAIT() do { asm volatile("s_waitcnt lgkmcnt(0)" ::: "memory"); SBAR(); } while (0)
; #define PVEXP(P, B, N) do { _Pragma("unroll") for (int r = (B); r < (B) + (N); ++r) P[r] = __builtin_amdgcn_exp2f(P[r]); } while (0)
; __device__ __forceinline__ void expHalf(f32x16& p0) {
; #pragma unroll
;     for (int r = 0; r < 16; ++r) p0[r] = __builtin_amdgcn_exp2f(p0[r]);
; }
; __device__ __forceinline__ void finishSM(f32x16& p0, f32x16& p1, float& l_reg, bf16x8& pa0, bf16x8& pa1, bf16x8& pa2, bf16x8& pa3) {
;     float ps = 0;
; #pragma unroll
;     for (int r = 0; r < 16; ++r) ps += p0[r];
; #pragma unroll
;     for (int r = 0; r < 16; ++r) ps += p1[r];
;     l_reg += ps;
;     ...
;     PK4(p0, 0, pa0); PK4(p0, 8, pa1); PK4(p1, 0, pa2); PK4(p1, 8, pa3);
; template <int NB> __device__ __forceinline__ void pv_blocks(f32x16* o, int vb, bf16x8 pa0, bf16x8 pa1, bf16x8 pa2, bf16x8 pa3, f32x16& pe0, f32x16& pe1) {
;     s16x4 x[8], y[8];
;     ...
;     PVLOAD(0, x); PVWAIT();
;     if (NB == 4) {
;         PVLOAD(1, y); SBAR(); PVMMA(o[0], x); PVEXP(pe0, 0, 8); SBAR(); PVWAIT();
;         PVLOAD(2, x); SBAR(); PVMMA(o[1], y); PVEXP(pe0, 8, 8); SBAR(); PVWAIT();
;         PVLOAD(3, y); SBAR(); PVMMA(o[2], x); PVEXP(pe1, 0, 8); SBAR(); PVWAIT();
;         PVMMA(o[3], y); PVEXP(pe1, 8, 8);
;     } else {
;         PVLOAD(1, y); SBAR(); PVMMA(o[0], x); PVEXP(pe0, 0, 16); SBAR(); PVWAIT();
;         PVMMA(o[1], y); PVEXP(pe1, 0, 16);
;     }
.Lat_far_g1p:
	v_exp_f32_e32 v112, v112
	v_exp_f32_e32 v113, v113
	v_exp_f32_e32 v114, v114
	v_add_f32_e32 v64, v64, v112
	v_exp_f32_e32 v115, v115
	v_add_f32_e32 v65, v65, v113
	v_exp_f32_e32 v116, v116
	v_add_f32_e32 v66, v66, v114
	v_exp_f32_e32 v117, v117
	v_add_f32_e32 v67, v67, v115
	v_exp_f32_e32 v118, v118
	v_add_f32_e32 v64, v64, v116
	v_exp_f32_e32 v119, v119
	v_add_f32_e32 v65, v65, v117
	v_exp_f32_e32 v120, v120
	v_add_f32_e32 v66, v66, v118
	v_exp_f32_e32 v121, v121
	v_add_f32_e32 v67, v67, v119
	v_exp_f32_e32 v122, v122
	v_add_f32_e32 v64, v64, v120
	v_exp_f32_e32 v123, v123
	v_add_f32_e32 v65, v65, v121
	v_exp_f32_e32 v124, v124
	v_add_f32_e32 v66, v66, v122
	v_exp_f32_e32 v125, v125
	v_add_f32_e32 v67, v67, v123
	v_exp_f32_e32 v126, v126
	v_add_f32_e32 v64, v64, v124
	v_exp_f32_e32 v127, v127
	v_add_f32_e32 v65, v65, v125
	v_exp_f32_e32 v192, v192
	v_add_f32_e32 v66, v66, v126
	v_cvt_pk_bf16_f32 v208, v112, v113
	v_exp_f32_e32 v193, v193
	v_add_f32_e32 v67, v67, v127
	v_cvt_pk_bf16_f32 v209, v114, v115
	v_exp_f32_e32 v194, v194
	v_add_f32_e32 v64, v64, v192
	v_cvt_pk_bf16_f32 v210, v116, v117
	v_exp_f32_e32 v195, v195
	v_add_f32_e32 v65, v65, v193
	v_cvt_pk_bf16_f32 v211, v118, v119
	v_exp_f32_e32 v196, v196
	v_add_f32_e32 v66, v66, v194
	v_cvt_pk_bf16_f32 v212, v120, v121
	v_exp_f32_e32 v197, v197
	v_add_f32_e32 v67, v67, v195
	v_cvt_pk_bf16_f32 v213, v122, v123
	v_exp_f32_e32 v198, v198
	v_add_f32_e32 v64, v64, v196
	v_cvt_pk_bf16_f32 v214, v124, v125
	v_exp_f32_e32 v199, v199
	v_add_f32_e32 v65, v65, v197
	v_cvt_pk_bf16_f32 v215, v126, v127
	v_exp_f32_e32 v200, v200
	v_add_f32_e32 v66, v66, v198
	v_exp_f32_e32 v201, v201
	v_add_f32_e32 v67, v67, v199
	v_exp_f32_e32 v202, v202
	v_add_f32_e32 v64, v64, v200
	v_cvt_pk_bf16_f32 v216, v192, v193
	v_exp_f32_e32 v203, v203
	v_add_f32_e32 v65, v65, v201
	v_cvt_pk_bf16_f32 v217, v194, v195
	v_exp_f32_e32 v204, v204
	v_add_f32_e32 v66, v66, v202
	v_cvt_pk_bf16_f32 v218, v196, v197
	v_exp_f32_e32 v205, v205
	v_add_f32_e32 v67, v67, v203
	v_cvt_pk_bf16_f32 v219, v198, v199
	v_exp_f32_e32 v206, v206
	v_add_f32_e32 v64, v64, v204
	v_cvt_pk_bf16_f32 v220, v200, v201
	v_exp_f32_e32 v207, v207
	v_add_f32_e32 v65, v65, v205
	v_cvt_pk_bf16_f32 v221, v202, v203
	v_add_f32_e32 v66, v66, v206
	v_add_f32_e32 v67, v67, v207
	v_cvt_pk_bf16_f32 v222, v204, v205
	v_cvt_pk_bf16_f32 v223, v206, v207
	s_nop 1
	s_waitcnt vmcnt(0)
	s_barrier
	s_setprio 0
	ds_read_b64_tr_b16 v[84:85], v168 offset:0
	ds_read_b64_tr_b16 v[86:87], v168 offset:2048
	ds_read_b64_tr_b16 v[88:89], v168 offset:4096
	ds_read_b64_tr_b16 v[90:91], v168 offset:6144
	ds_read_b64_tr_b16 v[92:93], v168 offset:8192
	ds_read_b64_tr_b16 v[94:95], v168 offset:10240
	ds_read_b64_tr_b16 v[128:129], v168 offset:12288
	ds_read_b64_tr_b16 v[130:131], v168 offset:14336
	ds_read_b64_tr_b16 v[132:133], v168 offset:512
	ds_read_b64_tr_b16 v[134:135], v168 offset:2560
	ds_read_b64_tr_b16 v[140:141], v168 offset:4608
	ds_read_b64_tr_b16 v[142:143], v168 offset:6656
	ds_read_b64_tr_b16 v[152:153], v168 offset:8704
	ds_read_b64_tr_b16 v[154:155], v168 offset:10752
	s_waitcnt lgkmcnt(12)
	v_mfma_f32_32x32x16_bf16 v[0:15], v[208:211], v[84:87], v[0:15]
	ds_read_b64_tr_b16 v[160:161], v168 offset:12800
	ds_read_b64_tr_b16 v[162:163], v168 offset:14848
	s_waitcnt lgkmcnt(12)
	v_mfma_f32_32x32x16_bf16 v[0:15], v[212:215], v[88:91], v[0:15]
	ds_read_b64_tr_b16 v[84:85], v168 offset:1024
	ds_read_b64_tr_b16 v[86:87], v168 offset:3072
	s_waitcnt lgkmcnt(12)
	v_mfma_f32_32x32x16_bf16 v[0:15], v[216:219], v[92:95], v[0:15]
	ds_read_b64_tr_b16 v[88:89], v168 offset:5120
	ds_read_b64_tr_b16 v[90:91], v168 offset:7168
	s_waitcnt lgkmcnt(12)
	v_mfma_f32_32x32x16_bf16 v[0:15], v[220:223], v[128:131], v[0:15]
	ds_read_b64_tr_b16 v[92:93], v168 offset:9216
	ds_read_b64_tr_b16 v[94:95], v168 offset:11264
	s_waitcnt lgkmcnt(12)
	v_mfma_f32_32x32x16_bf16 v[16:31], v[208:211], v[132:135], v[16:31]
	ds_read_b64_tr_b16 v[128:129], v168 offset:13312
	ds_read_b64_tr_b16 v[130:131], v168 offset:15360
	s_waitcnt lgkmcnt(12)
	v_mfma_f32_32x32x16_bf16 v[16:31], v[212:215], v[140:143], v[16:31]
	ds_read_b64_tr_b16 v[132:133], v168 offset:1536
	ds_read_b64_tr_b16 v[134:135], v168 offset:3584
	s_waitcnt lgkmcnt(12)
	v_mfma_f32_32x32x16_bf16 v[16:31], v[216:219], v[152:155], v[16:31]
	ds_read_b64_tr_b16 v[140:141], v168 offset:5632
	ds_read_b64_tr_b16 v[142:143], v168 offset:7680
	s_waitcnt lgkmcnt(12)
	v_mfma_f32_32x32x16_bf16 v[16:31], v[220:223], v[160:163], v[16:31]
	ds_read_b64_tr_b16 v[152:153], v168 offset:9728
	ds_read_b64_tr_b16 v[154:155], v168 offset:11776
	s_waitcnt lgkmcnt(12)
	v_mfma_f32_32x32x16_bf16 v[32:47], v[208:211], v[84:87], v[32:47]
	ds_read_b64_tr_b16 v[160:161], v168 offset:13824
	ds_read_b64_tr_b16 v[162:163], v168 offset:15872
	v_xor_b32_e32 v168, 0x4000, v168
	s_waitcnt lgkmcnt(12)
	v_mfma_f32_32x32x16_bf16 v[32:47], v[212:215], v[88:91], v[32:47]
	s_waitcnt lgkmcnt(10)
	v_mfma_f32_32x32x16_bf16 v[32:47], v[216:219], v[92:95], v[32:47]
	s_waitcnt lgkmcnt(8)
	v_mfma_f32_32x32x16_bf16 v[32:47], v[220:223], v[128:131], v[32:47]
	s_waitcnt lgkmcnt(6)
	v_mfma_f32_32x32x16_bf16 v[48:63], v[208:211], v[132:135], v[48:63]
	s_waitcnt lgkmcnt(4)
	v_mfma_f32_32x32x16_bf16 v[48:63], v[212:215], v[140:143], v[48:63]
	s_waitcnt lgkmcnt(2)
	v_mfma_f32_32x32x16_bf16 v[48:63], v[216:219], v[152:155], v[48:63]
	s_waitcnt lgkmcnt(0)
	v_mfma_f32_32x32x16_bf16 v[48:63], v[220:223], v[160:163], v[48:63]
	s_waitcnt vmcnt(0)
	s_barrier
